# hy_transpose phase: issue all 16 channel loads before one wait (was 8 serial load-pair/wait/ds_write rounds)
# baseline (speedup 1.0000x reference)
; #define LAS __attribute__((address_space(3)))
; __device__ __forceinline__ void hy_transpose(CArgsP a, int l, LAS unsigned char* lds) {
;     ...
;     for (int it = gw; it < nitems; it += NGW) {
;         const int rb = it >> 3, cb = it & 7, row0 = rb * 64, c0 = cb * 64;
; #pragma unroll
;         for (int j = 0; j < 16; ++j) { const int ch = 4 * j + (lane >> 4), rr = (lane & 15) * 4;
;             *(LAS u32x2*)(T + ch * 68 + rr) = *(const u32x2*)(HYT + (size_t)(c0 + ch) * RT + row0 + rr); }
;         asm volatile("s_waitcnt lgkmcnt(0)" ::: "memory");
; #pragma unroll
;         for (int j = 0; j < 8; ++j) { const int rr = 8 * j + (lane >> 3), k8 = (lane & 7) * 8; unsigned short e[8];
; #pragma unroll
;             for (int i = 0; i < 8; ++i) e[i] = T[(k8 + i) * 68 + rr];
;             u32x4 w; w.x = e[0] | ((unsigned)e[1] << 16); w.y = e[2] | ((unsigned)e[3] << 16); w.z = e[4] | ((unsigned)e[5] << 16); w.w = e[6] | ((unsigned)e[7] << 16);
;             *(u32x4*)(Y + (size_t)(row0 + rr) * DM + 1024 + c0 + k8) = w; }
.LBB0_216:
	s_and_b32 s18, s29, 0x1c0
	s_and_b32 s16, s30, 0xffffffc0
	s_ashr_i32 s17, s16, 31
	v_lshl_add_u64 v[0:1], s[16:17], 1, v[4:5]
	v_or_b32_e32 v40, s18, v8
	v_mul_u32_u24_e32 v40, 0x9000, v40
	v_lshlrev_b32_e32 v208, 1, v40
	v_lshl_add_u64 v[40:41], v[0:1], 0, v[208:209]
	global_load_dwordx2 v[80:81], v[40:41], off
	v_or_b32_e32 v42, s18, v12
	v_mul_u32_u24_e32 v42, 0x9000, v42
	v_lshlrev_b32_e32 v208, 1, v42
	v_lshl_add_u64 v[42:43], v[0:1], 0, v[208:209]
	global_load_dwordx2 v[82:83], v[42:43], off
	v_or_b32_e32 v44, s18, v13
	v_mul_u32_u24_e32 v44, 0x9000, v44
	v_lshlrev_b32_e32 v208, 1, v44
	v_lshl_add_u64 v[44:45], v[0:1], 0, v[208:209]
	global_load_dwordx2 v[84:85], v[44:45], off
	v_or_b32_e32 v46, s18, v14
	v_mul_u32_u24_e32 v46, 0x9000, v46
	v_lshlrev_b32_e32 v208, 1, v46
	v_lshl_add_u64 v[46:47], v[0:1], 0, v[208:209]
	global_load_dwordx2 v[86:87], v[46:47], off
	v_or_b32_e32 v48, s18, v15
	v_mul_u32_u24_e32 v48, 0x9000, v48
	v_lshlrev_b32_e32 v208, 1, v48
	v_lshl_add_u64 v[48:49], v[0:1], 0, v[208:209]
	global_load_dwordx2 v[88:89], v[48:49], off
	v_or_b32_e32 v50, s18, v16
	v_mul_u32_u24_e32 v50, 0x9000, v50
	v_lshlrev_b32_e32 v208, 1, v50
	v_lshl_add_u64 v[50:51], v[0:1], 0, v[208:209]
	global_load_dwordx2 v[90:91], v[50:51], off
	v_or_b32_e32 v52, s18, v17
	v_mul_u32_u24_e32 v52, 0x9000, v52
	v_lshlrev_b32_e32 v208, 1, v52
	v_lshl_add_u64 v[52:53], v[0:1], 0, v[208:209]
	global_load_dwordx2 v[92:93], v[52:53], off
	v_or_b32_e32 v54, s18, v18
	v_mul_u32_u24_e32 v54, 0x9000, v54
	v_lshlrev_b32_e32 v208, 1, v54
	v_lshl_add_u64 v[54:55], v[0:1], 0, v[208:209]
	global_load_dwordx2 v[94:95], v[54:55], off
	v_or_b32_e32 v56, s18, v19
	v_mul_u32_u24_e32 v56, 0x9000, v56
	v_lshlrev_b32_e32 v208, 1, v56
	v_lshl_add_u64 v[56:57], v[0:1], 0, v[208:209]
	global_load_dwordx2 v[96:97], v[56:57], off
	v_or_b32_e32 v58, s18, v20
	v_mul_u32_u24_e32 v58, 0x9000, v58
	v_lshlrev_b32_e32 v208, 1, v58
	v_lshl_add_u64 v[58:59], v[0:1], 0, v[208:209]
	global_load_dwordx2 v[98:99], v[58:59], off
	v_or_b32_e32 v60, s18, v21
	v_mul_u32_u24_e32 v60, 0x9000, v60
	v_lshlrev_b32_e32 v208, 1, v60
	v_lshl_add_u64 v[60:61], v[0:1], 0, v[208:209]
	global_load_dwordx2 v[100:101], v[60:61], off
	v_or_b32_e32 v62, s18, v22
	v_mul_u32_u24_e32 v62, 0x9000, v62
	v_lshlrev_b32_e32 v208, 1, v62
	v_lshl_add_u64 v[62:63], v[0:1], 0, v[208:209]
	global_load_dwordx2 v[102:103], v[62:63], off
	v_or_b32_e32 v64, s18, v23
	v_mul_u32_u24_e32 v64, 0x9000, v64
	v_lshlrev_b32_e32 v208, 1, v64
	v_lshl_add_u64 v[64:65], v[0:1], 0, v[208:209]
	global_load_dwordx2 v[104:105], v[64:65], off
	v_or_b32_e32 v66, s18, v24
	v_mul_u32_u24_e32 v66, 0x9000, v66
	v_lshlrev_b32_e32 v208, 1, v66
	v_lshl_add_u64 v[66:67], v[0:1], 0, v[208:209]
	global_load_dwordx2 v[106:107], v[66:67], off
	v_or_b32_e32 v68, s18, v25
	v_mul_u32_u24_e32 v68, 0x9000, v68
	v_lshlrev_b32_e32 v208, 1, v68
	v_lshl_add_u64 v[68:69], v[0:1], 0, v[208:209]
	global_load_dwordx2 v[108:109], v[68:69], off
	v_or_b32_e32 v70, s18, v26
	v_mul_u32_u24_e32 v70, 0x9000, v70
	v_lshlrev_b32_e32 v208, 1, v70
	v_lshl_add_u64 v[70:71], v[0:1], 0, v[208:209]
	global_load_dwordx2 v[110:111], v[70:71], off
	s_add_i32 s28, s28, s33
	s_add_i32 s29, s29, s71
	v_add_u32_e32 v112, 0x800, v33
	v_add_u32_e32 v113, 0x1000, v33
	v_add_u32_e32 v114, 0x1800, v33
	s_lshl_b32 s18, s18, 1
	s_waitcnt vmcnt(0)
	ds_write2_b64 v33, v[80:81], v[82:83] offset1:68
	ds_write2_b64 v33, v[84:85], v[86:87] offset0:136 offset1:204
	ds_write2_b64 v112, v[88:89], v[90:91] offset0:16 offset1:84
	ds_write2_b64 v112, v[92:93], v[94:95] offset0:152 offset1:220
	ds_write2_b64 v113, v[96:97], v[98:99] offset0:32 offset1:100
	ds_write2_b64 v113, v[100:101], v[102:103] offset0:168 offset1:236
	ds_write2_b64 v114, v[104:105], v[106:107] offset0:48 offset1:116
	ds_write2_b64 v114, v[108:109], v[110:111] offset0:184 offset1:252
	s_waitcnt lgkmcnt(0)
	ds_read_u16 v0, v11 offset:136
	ds_read_u16 v1, v11 offset:272
	ds_read_u16 v7, v11 offset:408
	ds_read_u16 v2, v11 offset:544
	ds_read_u16 v34, v11 offset:680
	ds_read_u16 v3, v11 offset:816
	ds_read_u16 v35, v11 offset:952
	s_waitcnt lgkmcnt(4)
	v_perm_b32 v1, v7, v1, s24
	ds_read_u16 v7, v11
	ds_read_u16 v36, v11 offset:16
	s_waitcnt lgkmcnt(4)
	v_perm_b32 v2, v34, v2, s24
	v_or_b32_e32 v34, s16, v9
	s_waitcnt lgkmcnt(2)
	v_perm_b32 v3, v35, v3, s24
	v_ashrrev_i32_e32 v35, 31, v34
	v_lshlrev_b64 v[34:35], 12, v[34:35]
	v_lshl_add_u64 v[34:35], s[72:73], 0, v[34:35]
	s_waitcnt lgkmcnt(1)
	v_perm_b32 v0, v0, v7, s24
	v_lshl_add_u64 v[34:35], v[34:35], 0, s[18:19]
	v_mov_b32_e32 v7, v209
	v_lshl_add_u64 v[34:35], v[34:35], 0, v[6:7]
	v_add_co_u32_e32 v34, vcc, s25, v34
	s_nop 1
	v_addc_co_u32_e32 v35, vcc, 0, v35, vcc
	global_store_dwordx4 v[34:35], v[0:3], off offset:2048
	ds_read_u16 v0, v11 offset:152
	ds_read_u16 v1, v11 offset:288
	ds_read_u16 v34, v11 offset:424
	ds_read_u16 v2, v11 offset:560
	ds_read_u16 v35, v11 offset:696
	ds_read_u16 v3, v11 offset:832
	ds_read_u16 v37, v11 offset:968
	s_waitcnt lgkmcnt(4)
	v_perm_b32 v1, v34, v1, s24
	v_or_b32_e32 v34, s16, v27
	s_waitcnt lgkmcnt(2)
	v_perm_b32 v2, v35, v2, s24
	v_ashrrev_i32_e32 v35, 31, v34
	v_lshlrev_b64 v[34:35], 12, v[34:35]
	v_lshl_add_u64 v[34:35], s[72:73], 0, v[34:35]
	v_lshl_add_u64 v[34:35], v[34:35], 0, s[18:19]
	v_lshl_add_u64 v[34:35], v[34:35], 0, v[6:7]
	v_add_co_u32_e32 v34, vcc, s25, v34
	s_waitcnt lgkmcnt(0)
; __device__ __forceinline__ void hy_transpose(CArgsP a, int l, LAS unsigned char* lds) {
;     ...
;         for (int j = 0; j < 8; ++j) { const int rr = 8 * j + (lane >> 3), k8 = (lane & 7) * 8; unsigned short e[8];
; #pragma unroll
;             for (int i = 0; i < 8; ++i) e[i] = T[(k8 + i) * 68 + rr];
;             u32x4 w; w.x = e[0] | ((unsigned)e[1] << 16); w.y = e[2] | ((unsigned)e[3] << 16); w.z = e[4] | ((unsigned)e[5] << 16); w.w = e[6] | ((unsigned)e[7] << 16);
;             *(u32x4*)(Y + (size_t)(row0 + rr) * DM + 1024 + c0 + k8) = w; }
	v_perm_b32 v3, v37, v3, s24
	v_perm_b32 v0, v0, v36, s24
	v_addc_co_u32_e32 v35, vcc, 0, v35, vcc
	global_store_dwordx4 v[34:35], v[0:3], off offset:2048
	ds_read_u16 v0, v11 offset:168
	ds_read_u16 v1, v11 offset:304
	ds_read_u16 v34, v11 offset:440
	ds_read_u16 v2, v11 offset:576
	ds_read_u16 v35, v11 offset:712
	ds_read_u16 v3, v11 offset:848
	ds_read_u16 v36, v11 offset:984
	s_waitcnt lgkmcnt(4)
	v_perm_b32 v1, v34, v1, s24
	s_waitcnt lgkmcnt(2)
	v_perm_b32 v2, v35, v2, s24
	s_waitcnt lgkmcnt(0)
	v_perm_b32 v3, v36, v3, s24
	ds_read_u16 v34, v11 offset:32
	ds_read_u16 v36, v11 offset:48
	s_waitcnt lgkmcnt(1)
	v_perm_b32 v0, v0, v34, s24
	v_or_b32_e32 v34, s16, v28
	v_ashrrev_i32_e32 v35, 31, v34
	v_lshlrev_b64 v[34:35], 12, v[34:35]
	v_lshl_add_u64 v[34:35], s[72:73], 0, v[34:35]
	v_lshl_add_u64 v[34:35], v[34:35], 0, s[18:19]
	v_lshl_add_u64 v[34:35], v[34:35], 0, v[6:7]
	v_add_co_u32_e32 v34, vcc, s25, v34
	s_nop 1
	v_addc_co_u32_e32 v35, vcc, 0, v35, vcc
	global_store_dwordx4 v[34:35], v[0:3], off offset:2048
	ds_read_u16 v0, v11 offset:184
	ds_read_u16 v1, v11 offset:320
	ds_read_u16 v34, v11 offset:456
	ds_read_u16 v2, v11 offset:592
	ds_read_u16 v35, v11 offset:728
	ds_read_u16 v3, v11 offset:864
	ds_read_u16 v37, v11 offset:1000
	s_waitcnt lgkmcnt(4)
	v_perm_b32 v1, v34, v1, s24
	v_or_b32_e32 v34, s16, v29
	s_waitcnt lgkmcnt(2)
	v_perm_b32 v2, v35, v2, s24
	v_ashrrev_i32_e32 v35, 31, v34
	v_lshlrev_b64 v[34:35], 12, v[34:35]
	v_lshl_add_u64 v[34:35], s[72:73], 0, v[34:35]
	v_lshl_add_u64 v[34:35], v[34:35], 0, s[18:19]
	v_lshl_add_u64 v[34:35], v[34:35], 0, v[6:7]
	v_add_co_u32_e32 v34, vcc, s25, v34
	s_waitcnt lgkmcnt(0)
	v_perm_b32 v3, v37, v3, s24
	v_perm_b32 v0, v0, v36, s24
	v_addc_co_u32_e32 v35, vcc, 0, v35, vcc
	global_store_dwordx4 v[34:35], v[0:3], off offset:2048
	ds_read_u16 v0, v11 offset:64
	ds_read_u16 v34, v11 offset:200
	ds_read_u16 v1, v11 offset:336
	ds_read_u16 v35, v11 offset:472
	ds_read_u16 v2, v11 offset:608
	ds_read_u16 v36, v11 offset:744
	ds_read_u16 v3, v11 offset:880
	ds_read_u16 v37, v11 offset:1016
	s_waitcnt lgkmcnt(6)
	v_perm_b32 v0, v34, v0, s24
	v_or_b32_e32 v34, s16, v30
	s_waitcnt lgkmcnt(4)
	v_perm_b32 v1, v35, v1, s24
	v_ashrrev_i32_e32 v35, 31, v34
	v_lshlrev_b64 v[34:35], 12, v[34:35]
	v_lshl_add_u64 v[34:35], s[72:73], 0, v[34:35]
	v_lshl_add_u64 v[34:35], v[34:35], 0, s[18:19]
	v_lshl_add_u64 v[34:35], v[34:35], 0, v[6:7]
	v_add_co_u32_e32 v34, vcc, s25, v34
	s_waitcnt lgkmcnt(0)
	v_perm_b32 v3, v37, v3, s24
	v_perm_b32 v2, v36, v2, s24
	v_addc_co_u32_e32 v35, vcc, 0, v35, vcc
	global_store_dwordx4 v[34:35], v[0:3], off offset:2048
	ds_read_u16 v0, v11 offset:80
	ds_read_u16 v34, v11 offset:216
	ds_read_u16 v1, v11 offset:352
	ds_read_u16 v35, v11 offset:488
	ds_read_u16 v2, v11 offset:624
	ds_read_u16 v36, v11 offset:760
	ds_read_u16 v3, v11 offset:896
	ds_read_u16 v37, v11 offset:1032
	s_waitcnt lgkmcnt(6)
	v_perm_b32 v0, v34, v0, s24
	v_or_b32_e32 v34, s16, v31
	s_waitcnt lgkmcnt(4)
	v_perm_b32 v1, v35, v1, s24
	v_ashrrev_i32_e32 v35, 31, v34
	v_lshlrev_b64 v[34:35], 12, v[34:35]
	v_lshl_add_u64 v[34:35], s[72:73], 0, v[34:35]
	v_lshl_add_u64 v[34:35], v[34:35], 0, s[18:19]
	v_lshl_add_u64 v[34:35], v[34:35], 0, v[6:7]
	v_add_co_u32_e32 v34, vcc, s25, v34
	s_waitcnt lgkmcnt(0)
	v_perm_b32 v3, v37, v3, s24
	v_perm_b32 v2, v36, v2, s24
	v_addc_co_u32_e32 v35, vcc, 0, v35, vcc
	global_store_dwordx4 v[34:35], v[0:3], off offset:2048
	ds_read_u16 v0, v11 offset:96
	ds_read_u16 v34, v11 offset:232
	ds_read_u16 v1, v11 offset:368
	ds_read_u16 v35, v11 offset:504
	ds_read_u16 v2, v11 offset:640
	ds_read_u16 v36, v11 offset:776
	ds_read_u16 v3, v11 offset:912
	ds_read_u16 v37, v11 offset:1048
	s_waitcnt lgkmcnt(6)
	v_perm_b32 v0, v34, v0, s24
	v_or_b32_e32 v34, s16, v32
	s_waitcnt lgkmcnt(4)
	v_perm_b32 v1, v35, v1, s24
	v_ashrrev_i32_e32 v35, 31, v34
	v_lshlrev_b64 v[34:35], 12, v[34:35]
	v_lshl_add_u64 v[34:35], s[72:73], 0, v[34:35]
	v_lshl_add_u64 v[34:35], v[34:35], 0, s[18:19]
	v_lshl_add_u64 v[34:35], v[34:35], 0, v[6:7]
	v_add_co_u32_e32 v34, vcc, s25, v34
	s_waitcnt lgkmcnt(0)
	v_perm_b32 v3, v37, v3, s24
	v_perm_b32 v2, v36, v2, s24
	v_addc_co_u32_e32 v35, vcc, 0, v35, vcc
	global_store_dwordx4 v[34:35], v[0:3], off offset:2048
	ds_read_u16 v0, v11 offset:112
	ds_read_u16 v34, v11 offset:248
	ds_read_u16 v1, v11 offset:384
	ds_read_u16 v35, v11 offset:520
	ds_read_u16 v2, v11 offset:656
	ds_read_u16 v36, v11 offset:792
	ds_read_u16 v3, v11 offset:928
	ds_read_u16 v37, v11 offset:1064
	s_waitcnt lgkmcnt(6)
	v_perm_b32 v0, v34, v0, s24
	v_or_b32_e32 v34, s30, v10
	s_waitcnt lgkmcnt(4)
	v_perm_b32 v1, v35, v1, s24
	v_ashrrev_i32_e32 v35, 31, v34
	v_lshlrev_b64 v[34:35], 12, v[34:35]
	v_lshl_add_u64 v[34:35], s[72:73], 0, v[34:35]
	v_lshl_add_u64 v[34:35], v[34:35], 0, s[18:19]
	v_lshl_add_u64 v[34:35], v[34:35], 0, v[6:7]
	v_add_co_u32_e32 v34, vcc, 0x6600000, v34
	s_waitcnt lgkmcnt(0)
	v_perm_b32 v3, v37, v3, s24
	v_perm_b32 v2, v36, v2, s24
	v_addc_co_u32_e32 v35, vcc, 0, v35, vcc
	global_store_dwordx4 v[34:35], v[0:3], off offset:2048
	s_waitcnt lgkmcnt(0)
	s_add_i32 s30, s30, s84
	s_cmp_ge_i32 s28, s15
	s_cbranch_scc0 .LBB0_216
